# speedup vs baseline: 1.0076x; 1.0054x over previous
; #define LAS __attribute__((address_space(3)))
; __device__ __forceinline__ unsigned pk2(float lo, float hi) { return f2bf(lo) | (f2bf(hi) << 16); }
; #define MFMA16(a, b, c) __builtin_amdgcn_mfma_f32_16x16x32_bf16((a), (b), (c), 0, 0, 0)
; template <int KIND, int MODE>
; __device__ __forceinline__ void scan_unit(Frame& F, int layer, int h, int vhalf, int grp) {
;     ...
;             for (int tt = 0; tt < 4; ++tt) { const int t = 16 * tt + li; f32x4 oi = (f32x4){0.f, 0.f, 0.f, 0.f}, oe = (f32x4){0.f, 0.f, 0.f, 0.f};
; #pragma unroll
;                 for (int ks = 0; ks < 2; ++ks) { const bf16x8 pb = *(const LAS bf16x8*)(PS + t * PST + 32 * ks + 8 * g); oi = MFMA16(vf[ks], pb, oi); }
; #pragma unroll
;                 for (int i = 0; i < NSL; ++i) { const u32x2 q0 = *(const LAS u32x2*)(QS + t * QST + 32 * i + 4 * g), q1 = *(const LAS u32x2*)(QS + t * QST + 32 * i + 16 + 4 * g);
;                     const bf16x8 qb = __builtin_bit_cast(bf16x8, ((u32x4){q0.x, q0.y, q1.x, q1.y})); oe = MFMA16(sf[i], qb, oe); }
;                 f32x4 o;
;                 if (KIND) { const float wi = X[128 + t]; float qn = wi * (((X[896 + t] + X[960 + t]) + (X[1024 + t] + X[1088 + t])) + ((X[1152 + t] + X[1216 + t]) + (X[1280 + t] + X[1344 + t])));
;                     qn += (X[640 + t] + X[704 + t]) + (X[768 + t] + X[832 + t]);
;                     const float inv = 1.0f / fmaxf(fabsf(qn), X[256 + t]); o = (oi + oe * wi) * inv; }
;                 else o = oi + oe;
;                 u32x2 ow; ow.x = pk2(o[0], o[1]); ow.y = pk2(o[2], o[3]); *(u32x2*)(yout + (size_t)(tb + t) * D) = ow;
;                 float sq = (o[0] * o[0] + o[1] * o[1]) + (o[2] * o[2] + o[3] * o[3]); sq += __shfl_xor(sq, 16); sq += __shfl_xor(sq, 32);
;                 if (g == 0) SSR[w * 64 + t] = sq;
.LBB0_538:
	s_or_b64 exec, exec, s[0:1]
	s_waitcnt lgkmcnt(0)
	ds_read_b128 v[108:111], v200
	ds_read_b128 v[112:115], v200 offset:64
	ds_read2_b64 v[208:211], v187 offset1:4
	ds_read2_b64 v[212:215], v187 offset0:8 offset1:12
	ds_read2_b64 v[216:219], v187 offset0:16 offset1:20
	ds_read2_b64 v[220:223], v187 offset0:24 offset1:28
	ds_read2_b64 v[236:239], v187 offset0:32 offset1:36
	ds_read2_b64 v[240:243], v187 offset0:40 offset1:44
	ds_read2_b64 v[244:247], v187 offset0:48 offset1:52
	ds_read2_b64 v[248:251], v187 offset0:56 offset1:60
	s_waitcnt lgkmcnt(6)
	v_mfma_f32_16x16x32_bf16 v[108:111], v[72:75], v[108:111], 0
	v_mfma_f32_16x16x32_bf16 v[208:211], v[76:79], v[208:211], 0
	v_mfma_f32_16x16x32_bf16 v[208:211], v[80:83], v[212:215], v[208:211]
	s_waitcnt lgkmcnt(5)
	v_mfma_f32_16x16x32_bf16 v[208:211], v[84:87], v[216:219], v[208:211]
	s_waitcnt lgkmcnt(4)
	v_mfma_f32_16x16x32_bf16 v[208:211], v[88:91], v[220:223], v[208:211]
	s_waitcnt lgkmcnt(3)
	v_mfma_f32_16x16x32_bf16 v[208:211], v[92:95], v[236:239], v[208:211]
	s_waitcnt lgkmcnt(2)
	v_mfma_f32_16x16x32_bf16 v[208:211], v[96:99], v[240:243], v[208:211]
	s_waitcnt lgkmcnt(1)
	v_mfma_f32_16x16x32_bf16 v[208:211], v[100:103], v[244:247], v[208:211]
	s_waitcnt lgkmcnt(0)
	v_mfma_f32_16x16x32_bf16 v[208:211], v[104:107], v[248:251], v[208:211]
	v_mfma_f32_16x16x32_bf16 v[108:111], v[68:71], v[112:115], v[108:111]
	ds_read2st64_b32 v[112:113], v188 offset0:2 offset1:4
	ds_read2st64_b32 v[114:115], v188 offset0:14 offset1:15
	ds_read2st64_b32 v[166:167], v188 offset0:16 offset1:17
	ds_read2st64_b32 v[212:213], v188 offset0:18 offset1:19
	ds_read2st64_b32 v[214:215], v188 offset0:20 offset1:21
	ds_read2st64_b32 v[216:217], v188 offset0:10 offset1:11
	ds_read2st64_b32 v[218:219], v188 offset0:12 offset1:13
	s_waitcnt lgkmcnt(0)
	v_add_f32_e32 v114, v114, v115
	v_add_f32_e32 v166, v166, v167
	v_add_f32_e32 v212, v212, v213
	v_add_f32_e32 v214, v214, v215
	v_mov_b32_e32 v115, v216
	v_mov_b32_e32 v167, v217
	v_mov_b32_e32 v213, v218
	v_mov_b32_e32 v215, v219
	v_pk_add_f32 v[114:115], v[114:115], v[166:167]
	v_pk_add_f32 v[166:167], v[212:213], v[214:215]
	v_max_f32_e32 v0, v113, v113
	v_pk_add_f32 v[114:115], v[114:115], v[166:167]
	s_nop 0
	v_fmac_f32_e32 v115, v112, v114
	v_max_f32_e64 v0, |v115|, v0
	v_div_scale_f32 v113, s[0:1], v0, v0, 1.0
	v_rcp_f32_e32 v114, v113
	s_nop 0
	v_fma_f32 v115, -v113, v114, 1.0
	v_fmac_f32_e32 v114, v115, v114
	v_div_scale_f32 v115, vcc, 1.0, v0, 1.0
	v_mul_f32_e32 v166, v115, v114
	v_fma_f32 v167, -v113, v166, v115
	v_fmac_f32_e32 v166, v167, v114
	v_fma_f32 v113, -v113, v166, v115
	v_div_fmas_f32 v113, v113, v114, v166
	v_div_fixup_f32 v0, v113, v0, 1.0
	v_pk_fma_f32 v[110:111], v[210:211], v[112:113], v[110:111] op_sel_hi:[1,0,1]
	v_pk_fma_f32 v[108:109], v[208:209], v[112:113], v[108:109] op_sel_hi:[1,0,1]
	v_pk_mul_f32 v[110:111], v[110:111], v[0:1] op_sel_hi:[1,0]
	v_pk_mul_f32 v[108:109], v[108:109], v[0:1] op_sel_hi:[1,0]
	v_cvt_pk_bf16_f32 v113, v110, v111
	v_mul_f32_e32 v0, v109, v109
	v_cvt_pk_bf16_f32 v112, v108, v109
	v_fmac_f32_e32 v0, v108, v108
	v_mul_f32_e32 v108, v111, v111
	v_fmac_f32_e32 v108, v110, v110
	v_add_f32_e32 v0, v0, v108
	ds_bpermute_b32 v108, v128, v0
	s_waitcnt lgkmcnt(0)
	v_add_f32_e32 v0, v0, v108
	ds_bpermute_b32 v108, v129, v0
	v_or_b32_e32 v114, s44, v186
	v_ashrrev_i32_e32 v115, 31, v114
	v_lshlrev_b64 v[114:115], 11, v[114:115]
	v_lshl_add_u64 v[114:115], v[2:3], 0, v[114:115]
	flat_store_dwordx2 v[114:115], v[112:113]
	s_and_saveexec_b64 s[0:1], s[12:13]
	s_cbranch_execz .LBB0_540
	s_waitcnt lgkmcnt(0)
	v_add_f32_e32 v0, v0, v108
	ds_write_b32 v185, v0 offset:64
; #define LAS __attribute__((address_space(3)))
; __device__ __forceinline__ unsigned pk2(float lo, float hi) { return f2bf(lo) | (f2bf(hi) << 16); }
; #define MFMA16(a, b, c) __builtin_amdgcn_mfma_f32_16x16x32_bf16((a), (b), (c), 0, 0, 0)
; template <int KIND, int MODE>
; __device__ __forceinline__ void scan_unit(Frame& F, int layer, int h, int vhalf, int grp) {
;     ...
;             for (int tt = 0; tt < 4; ++tt) { const int t = 16 * tt + li; f32x4 oi = (f32x4){0.f, 0.f, 0.f, 0.f}, oe = (f32x4){0.f, 0.f, 0.f, 0.f};
; #pragma unroll
;                 for (int ks = 0; ks < 2; ++ks) { const bf16x8 pb = *(const LAS bf16x8*)(PS + t * PST + 32 * ks + 8 * g); oi = MFMA16(vf[ks], pb, oi); }
; #pragma unroll
;                 for (int i = 0; i < NSL; ++i) { const u32x2 q0 = *(const LAS u32x2*)(QS + t * QST + 32 * i + 4 * g), q1 = *(const LAS u32x2*)(QS + t * QST + 32 * i + 16 + 4 * g);
;                     const bf16x8 qb = __builtin_bit_cast(bf16x8, ((u32x4){q0.x, q0.y, q1.x, q1.y})); oe = MFMA16(sf[i], qb, oe); }
;                 f32x4 o;
;                 if (KIND) { const float wi = X[128 + t]; float qn = wi * (((X[896 + t] + X[960 + t]) + (X[1024 + t] + X[1088 + t])) + ((X[1152 + t] + X[1216 + t]) + (X[1280 + t] + X[1344 + t])));
;                     qn += (X[640 + t] + X[704 + t]) + (X[768 + t] + X[832 + t]);
;                     const float inv = 1.0f / fmaxf(fabsf(qn), X[256 + t]); o = (oi + oe * wi) * inv; }
;                 else o = oi + oe;
;                 u32x2 ow; ow.x = pk2(o[0], o[1]); ow.y = pk2(o[2], o[3]); *(u32x2*)(yout + (size_t)(tb + t) * D) = ow;
;                 float sq = (o[0] * o[0] + o[1] * o[1]) + (o[2] * o[2] + o[3] * o[3]); sq += __shfl_xor(sq, 16); sq += __shfl_xor(sq, 32);
;                 if (g == 0) SSR[w * 64 + t] = sq;
.LBB0_540:
	s_or_b64 exec, exec, s[0:1]
	s_waitcnt lgkmcnt(0)
	ds_read_b128 v[108:111], v201
	ds_read_b128 v[112:115], v201 offset:64
	ds_read2_b64 v[208:211], v190 offset1:4
	ds_read2_b64 v[212:215], v190 offset0:8 offset1:12
	ds_read2_b64 v[216:219], v190 offset0:16 offset1:20
	ds_read2_b64 v[220:223], v190 offset0:24 offset1:28
	ds_read2_b64 v[236:239], v190 offset0:32 offset1:36
	ds_read2_b64 v[240:243], v190 offset0:40 offset1:44
	ds_read2_b64 v[244:247], v190 offset0:48 offset1:52
	ds_read2_b64 v[248:251], v190 offset0:56 offset1:60
	s_waitcnt lgkmcnt(6)
	v_mfma_f32_16x16x32_bf16 v[108:111], v[72:75], v[108:111], 0
	v_mfma_f32_16x16x32_bf16 v[208:211], v[76:79], v[208:211], 0
	v_mfma_f32_16x16x32_bf16 v[208:211], v[80:83], v[212:215], v[208:211]
	s_waitcnt lgkmcnt(5)
	v_mfma_f32_16x16x32_bf16 v[208:211], v[84:87], v[216:219], v[208:211]
	s_waitcnt lgkmcnt(4)
	v_mfma_f32_16x16x32_bf16 v[208:211], v[88:91], v[220:223], v[208:211]
	s_waitcnt lgkmcnt(3)
	v_mfma_f32_16x16x32_bf16 v[208:211], v[92:95], v[236:239], v[208:211]
	s_waitcnt lgkmcnt(2)
	v_mfma_f32_16x16x32_bf16 v[208:211], v[96:99], v[240:243], v[208:211]
	s_waitcnt lgkmcnt(1)
	v_mfma_f32_16x16x32_bf16 v[208:211], v[100:103], v[244:247], v[208:211]
	s_waitcnt lgkmcnt(0)
	v_mfma_f32_16x16x32_bf16 v[208:211], v[104:107], v[248:251], v[208:211]
	v_mfma_f32_16x16x32_bf16 v[108:111], v[68:71], v[112:115], v[108:111]
	ds_read2st64_b32 v[112:113], v191 offset0:2 offset1:4
	ds_read2st64_b32 v[114:115], v191 offset0:14 offset1:15
	ds_read2st64_b32 v[166:167], v191 offset0:16 offset1:17
	ds_read2st64_b32 v[212:213], v191 offset0:18 offset1:19
	ds_read2st64_b32 v[214:215], v191 offset0:20 offset1:21
	ds_read2st64_b32 v[216:217], v191 offset0:10 offset1:11
	ds_read2st64_b32 v[218:219], v191 offset0:12 offset1:13
	s_waitcnt lgkmcnt(0)
	v_add_f32_e32 v114, v114, v115
	v_add_f32_e32 v166, v166, v167
	v_add_f32_e32 v212, v212, v213
	v_add_f32_e32 v214, v214, v215
	v_mov_b32_e32 v115, v216
	v_mov_b32_e32 v167, v217
	v_mov_b32_e32 v213, v218
	v_mov_b32_e32 v215, v219
	v_pk_add_f32 v[114:115], v[114:115], v[166:167]
	v_pk_add_f32 v[166:167], v[212:213], v[214:215]
	v_max_f32_e32 v0, v113, v113
	v_pk_add_f32 v[114:115], v[114:115], v[166:167]
	s_nop 0
	v_fmac_f32_e32 v115, v112, v114
	v_max_f32_e64 v0, |v115|, v0
	v_div_scale_f32 v113, s[0:1], v0, v0, 1.0
	v_rcp_f32_e32 v114, v113
	s_nop 0
	v_fma_f32 v115, -v113, v114, 1.0
	v_fmac_f32_e32 v114, v115, v114
	v_div_scale_f32 v115, vcc, 1.0, v0, 1.0
	v_mul_f32_e32 v166, v115, v114
	v_fma_f32 v167, -v113, v166, v115
	v_fmac_f32_e32 v166, v167, v114
	v_fma_f32 v113, -v113, v166, v115
	v_div_fmas_f32 v113, v113, v114, v166
	v_div_fixup_f32 v0, v113, v0, 1.0
	v_pk_fma_f32 v[110:111], v[210:211], v[112:113], v[110:111] op_sel_hi:[1,0,1]
	v_pk_fma_f32 v[108:109], v[208:209], v[112:113], v[108:109] op_sel_hi:[1,0,1]
	v_pk_mul_f32 v[110:111], v[110:111], v[0:1] op_sel_hi:[1,0]
	v_pk_mul_f32 v[108:109], v[108:109], v[0:1] op_sel_hi:[1,0]
	v_cvt_pk_bf16_f32 v113, v110, v111
	v_mul_f32_e32 v0, v109, v109
	v_cvt_pk_bf16_f32 v112, v108, v109
	v_fmac_f32_e32 v0, v108, v108
	v_mul_f32_e32 v108, v111, v111
	v_fmac_f32_e32 v108, v110, v110
	v_add_f32_e32 v0, v0, v108
	ds_bpermute_b32 v108, v128, v0
	s_waitcnt lgkmcnt(0)
	v_add_f32_e32 v0, v0, v108
	ds_bpermute_b32 v108, v129, v0
	v_or_b32_e32 v114, s44, v189
	v_ashrrev_i32_e32 v115, 31, v114
	v_lshlrev_b64 v[114:115], 11, v[114:115]
	v_lshl_add_u64 v[114:115], v[2:3], 0, v[114:115]
	flat_store_dwordx2 v[114:115], v[112:113]
	s_and_saveexec_b64 s[0:1], s[12:13]
	s_cbranch_execz .LBB0_542
	s_waitcnt lgkmcnt(0)
	v_add_f32_e32 v0, v0, v108
	ds_write_b32 v185, v0 offset:128
